# gdnpre: kd0/kd1 transposed 2-byte stores staged through LDS and written as 16-byte coalesced stores
# speedup vs baseline: 1.0698x; 1.0000x over previous
.LBB0_241:
	s_or_b64 exec, exec, s[40:41]
	v_mul_f32_e32 v37, 0xbfb8aa3b, v28
	v_exp_f32_e32 v37, v37
	v_mul_f32_e32 v54, 0xbfb8aa3b, v29
	v_exp_f32_e32 v54, v54
	v_mul_f32_e32 v56, 0xbfb8aa3b, v27
	v_add_f32_e32 v37, 1.0, v37
	v_exp_f32_e32 v56, v56
	v_add_f32_e32 v55, 1.0, v54
	v_rcp_f32_e32 v54, v37
	v_mul_f32_e32 v37, 0xbfb8aa3b, v26
	v_rcp_f32_e32 v55, v55
	v_exp_f32_e32 v37, v37
	s_mov_b32 s0, 0x358637bd
	s_mov_b32 s2, 0x800000
	v_pk_mul_f32 v[70:71], v[28:29], v[54:55]
	v_add_f32_e32 v28, 1.0, v37
	v_add_f32_e32 v29, 1.0, v56
	v_mul_f32_e32 v37, 0xbfb8aa3b, v24
	v_mul_f32_e32 v54, 0xbfb8aa3b, v25
	v_rcp_f32_e32 v28, v28
	v_rcp_f32_e32 v29, v29
	v_exp_f32_e32 v37, v37
	v_exp_f32_e32 v54, v54
	s_waitcnt lgkmcnt(0)
	s_barrier
	v_pk_mul_f32 v[62:63], v[26:27], v[28:29]
	v_add_f32_e32 v26, 1.0, v37
	v_add_f32_e32 v27, 1.0, v54
	v_mul_f32_e32 v28, 0xbfb8aa3b, v22
	v_mul_f32_e32 v29, 0xbfb8aa3b, v23
	v_rcp_f32_e32 v26, v26
	v_rcp_f32_e32 v27, v27
	v_exp_f32_e32 v28, v28
	v_exp_f32_e32 v29, v29
	v_lshlrev_b32_e32 v37, 4, v69
	v_pk_mul_f32 v[60:61], v[24:25], v[26:27]
	v_add_f32_e32 v24, 1.0, v28
	v_add_f32_e32 v25, 1.0, v29
	v_rcp_f32_e32 v24, v24
	v_rcp_f32_e32 v25, v25
	v_mul_f32_e32 v26, 0xbfb8aa3b, v14
	v_mul_f32_e32 v27, 0xbfb8aa3b, v15
	v_exp_f32_e32 v26, v26
	v_exp_f32_e32 v27, v27
	v_pk_mul_f32 v[58:59], v[22:23], v[24:25]
	v_mul_f32_e32 v24, 0xbfb8aa3b, v16
	v_mul_f32_e32 v25, 0xbfb8aa3b, v17
	v_exp_f32_e32 v24, v24
	v_exp_f32_e32 v25, v25
	v_add_f32_e32 v22, 1.0, v26
	v_add_f32_e32 v23, 1.0, v27
	v_rcp_f32_e32 v22, v22
	v_rcp_f32_e32 v23, v23
	v_add_f32_e32 v24, 1.0, v24
	v_add_f32_e32 v25, 1.0, v25
	v_rcp_f32_e32 v24, v24
	v_rcp_f32_e32 v25, v25
	v_pk_mul_f32 v[56:57], v[14:15], v[22:23]
	s_waitcnt lgkmcnt(0)
	v_pk_add_f32 v[14:15], v[64:65], v[66:67]
	v_mul_f32_e32 v26, 0xbfb8aa3b, v18
	v_mul_f32_e32 v27, 0xbfb8aa3b, v19
	v_mul_f32_e32 v28, 0xbfb8aa3b, v20
	v_mul_f32_e32 v29, 0xbfb8aa3b, v21
	v_pk_add_f32 v[14:15], v[14:15], s[0:1] op_sel_hi:[1,0]
	v_exp_f32_e32 v26, v26
	v_exp_f32_e32 v27, v27
	v_exp_f32_e32 v28, v28
	v_exp_f32_e32 v29, v29
	v_pk_mul_f32 v[54:55], v[16:17], v[24:25]
	v_mul_f32_e32 v16, 0x4b800000, v15
	v_cmp_gt_f32_e64 s[0:1], s2, v15
	v_cmp_gt_f32_e64 s[40:41], s2, v14
	v_add_f32_e32 v26, 1.0, v26
	v_cndmask_b32_e64 v15, v15, v16, s[0:1]
	v_mul_f32_e32 v16, 0x4b800000, v14
	v_rsq_f32_e32 v15, v15
	v_cndmask_b32_e64 v14, v14, v16, s[40:41]
	v_rsq_f32_e32 v16, v14
	v_add_f32_e32 v27, 1.0, v27
	v_add_f32_e32 v28, 1.0, v28
	v_add_f32_e32 v29, 1.0, v29
	v_rcp_f32_e32 v26, v26
	v_rcp_f32_e32 v27, v27
	v_rcp_f32_e32 v28, v28
	v_rcp_f32_e32 v29, v29
	v_mul_f32_e32 v14, 0x45800000, v15
	v_cndmask_b32_e64 v14, v15, v14, s[0:1]
	v_mul_f32_e32 v15, 0x45800000, v16
	v_mul_f32_e32 v14, 0x3e000000, v14
	v_cndmask_b32_e64 v16, v16, v15, s[40:41]
	s_mul_i32 s0, s10, 0xa000
	v_pk_mul_f32 v[22:23], v[18:19], v[26:27]
	v_pk_mul_f32 v[18:19], v[20:21], v[28:29]
	v_pk_mul_f32 v[64:65], v[2:3], v[16:17] op_sel_hi:[1,0]
	v_pk_mul_f32 v[20:21], v[38:39], v[14:15] op_sel_hi:[1,0]
	v_mov_b32_e32 v38, s0
	v_lshl_add_u32 v2, v35, 2, 0
	s_add_i32 s0, 0, 0x11600
	v_pk_mul_f32 v[72:73], v[10:11], v[14:15] op_sel_hi:[1,0]
	v_add_u32_e32 v2, 0x11200, v2
	v_mov_b32_e32 v10, s0
	v_pk_mul_f32 v[4:5], v[4:5], v[14:15] op_sel_hi:[1,0]
	v_pk_mul_f32 v[66:67], v[6:7], v[14:15] op_sel_hi:[1,0]
	v_pk_mul_f32 v[76:77], v[50:51], v[14:15] op_sel_hi:[1,0]
	v_pk_mul_f32 v[78:79], v[44:45], v[16:17] op_sel_hi:[1,0]
	v_pk_mul_f32 v[50:51], v[46:47], v[14:15] op_sel_hi:[1,0]
	v_pk_mul_f32 v[44:45], v[42:43], v[14:15] op_sel_hi:[1,0]
	v_pk_mul_f32 v[30:31], v[30:31], v[14:15] op_sel_hi:[1,0]
	ds_read2st64_b32 v[2:3], v2 offset1:1
	ds_read_b64 v[14:15], v10
	v_mov_b32_e32 v39, v0
	v_lshl_add_u64 v[6:7], v[38:39], 1, s[24:25]
	v_lshlrev_b32_e32 v238, 1, v35
	v_and_b32_e32 v238, 24, v238
	v_and_b32_e32 v239, 32, v35
	v_lshrrev_b32_e32 v240, 2, v35
	v_and_b32_e32 v240, 4, v240
	v_or3_b32 v238, v238, v239, v240
	v_and_b32_e32 v239, 3, v35
	v_or_b32_e32 v238, v238, v239
	v_mul_u32_u24_e32 v241, 0x840, v69
	v_lshl_add_u32 v236, v238, 1, v241
	v_sub_u32_e32 v239, 63, v35
	v_lshlrev_b32_e32 v238, 1, v239
	v_and_b32_e32 v238, 24, v238
	v_and_b32_e32 v240, 32, v239
	v_or_b32_e32 v238, v238, v240
	v_lshrrev_b32_e32 v240, 2, v239
	v_and_b32_e32 v240, 4, v240
	v_and_b32_e32 v239, 3, v239
	v_or3_b32 v238, v238, v240, v239
	v_lshl_add_u32 v237, v238, 1, v241
	v_add_u32_e32 v237, 0x2100, v237
	v_lshlrev_b32_e32 v242, 4, v1
	v_lshl_add_u32 v242, v38, 1, v242
	v_add_u32_e32 v243, 0x10800, v242
	v_add_u32_e32 v242, 0x6800, v242
	v_pk_mul_f32 v[42:43], v[40:41], v[16:17] op_sel_hi:[1,0]
	s_waitcnt lgkmcnt(1)
	v_mul_f32_e32 v10, 0x3fb8aa3b, v2
	s_waitcnt lgkmcnt(0)
	v_sub_f32_e32 v2, v14, v2
	v_mul_f32_e32 v2, 0x3fb8aa3b, v2
	v_exp_f32_e32 v81, v2
	v_sub_f32_e32 v2, v15, v3
	v_mul_f32_e32 v2, 0x3fb8aa3b, v2
	v_exp_f32_e32 v82, v2
	v_lshlrev_b32_e32 v2, 6, v35
	v_exp_f32_e32 v39, v10
	v_mul_f32_e32 v10, 0x3fb8aa3b, v3
	v_ashrrev_i32_e32 v3, 31, v2
	v_lshl_add_u64 v[2:3], v[2:3], 1, v[6:7]
	s_mov_b64 s[0:1], 0x2000
	v_sub_u32_e32 v40, 63, v35
	v_lshl_add_u64 v[24:25], v[2:3], 0, s[0:1]
	v_lshlrev_b32_e32 v2, 6, v40
	v_pk_mul_f32 v[74:75], v[12:13], v[16:17] op_sel_hi:[1,0]
	v_ashrrev_i32_e32 v3, 31, v2
	v_lshlrev_b32_e32 v11, 1, v35
	v_lshrrev_b32_e32 v12, 2, v35
	v_exp_f32_e32 v80, v10
	v_lshl_add_u64 v[2:3], v[2:3], 1, v[6:7]
	s_mov_b64 s[0:1], 0xc000
	v_and_b32_e32 v10, 32, v35
	v_and_b32_e32 v11, 24, v11
	v_and_b32_e32 v12, 4, v12
	v_lshl_add_u64 v[26:27], v[2:3], 0, s[0:1]
	v_lshlrev_b32_e32 v2, 11, v69
	v_mov_b32_e32 v3, v0
	v_or3_b32 v10, v11, v10, v12
	v_lshlrev_b32_e32 v10, 1, v10
	v_mov_b32_e32 v11, v0
	v_lshl_add_u64 v[2:3], v[6:7], 0, v[2:3]
	v_lshl_add_u64 v[6:7], v[2:3], 0, v[10:11]
	v_lshrrev_b32_e32 v10, 1, v1
	v_and_b32_e32 v10, 6, v10
	v_lshl_add_u64 v[12:13], v[6:7], 0, v[10:11]
	v_lshlrev_b32_e32 v7, 1, v40
	v_lshrrev_b32_e32 v10, 2, v40
	v_and_b32_e32 v6, 32, v40
	v_and_b32_e32 v7, 24, v7
	v_and_b32_e32 v10, 4, v10
	v_or3_b32 v6, v7, v6, v10
	v_lshlrev_b32_e32 v6, 1, v6
	v_mov_b32_e32 v7, v0
	v_lshl_add_u64 v[2:3], v[2:3], 0, v[6:7]
	v_and_b32_e32 v6, 3, v40
	v_lshlrev_b32_e32 v6, 1, v6
	v_pk_mul_f32 v[46:47], v[48:49], v[16:17] op_sel_hi:[1,0]
	v_lshl_add_u64 v[48:49], v[2:3], 0, v[6:7]
	v_lshlrev_b32_e32 v3, 2, v69
	v_and_b32_e32 v2, 32, v37
	v_and_b32_e32 v6, 4, v3
	s_mov_b64 s[0:1], 0x6000
	v_or_b32_e32 v7, v2, v6
	v_pk_mul_f32 v[8:9], v[8:9], v[16:17] op_sel_hi:[1,0]
	v_pk_mul_f32 v[28:29], v[32:33], v[16:17] op_sel_hi:[1,0]
	v_pk_mul_f32 v[16:17], v[52:53], v[16:17] op_sel_hi:[1,0]
	v_lshl_add_u64 v[32:33], v[12:13], 0, s[0:1]
	s_mov_b64 s[0:1], 0x10000
	v_or_b32_e32 v83, v2, v3
	v_mul_f32_e32 v3, v4, v39
	v_lshlrev_b32_e32 v52, 1, v7
	v_mov_b32_e32 v53, v0
	v_or_b32_e32 v37, v6, v37
	v_cvt_pk_bf16_f32 v6, v70, v71
	v_cvt_pk_bf16_f32 v3, v3, s0
	v_lshl_add_u64 v[70:71], v[24:25], 0, v[52:53]
	v_and_b32_e32 v152, 0xffff, v3
	v_mul_f32_e32 v3, v4, v80
	v_cvt_pk_bf16_f32 v3, v3, s0
	v_lshl_add_u64 v[52:53], v[26:27], 0, v[52:53]
	v_and_b32_e32 v154, 0xffff, v3
	v_mul_f32_e32 v3, v64, v81
	v_lshl_add_u64 v[40:41], v[48:49], 0, s[0:1]
	v_cvt_pk_bf16_f32 v3, v3, s0
	v_add_co_u32_e64 v12, s[0:1], s19, v12
	v_cvt_pk_bf16_f32 v10, v4, v5
	s_nop 0
	v_addc_co_u32_e64 v13, s[0:1], 0, v13, s[0:1]
	ds_write_b16 v236, v3
	v_mul_f32_e32 v3, v64, v82
	v_cvt_pk_bf16_f32 v3, v3, s0
	s_mov_b32 s0, 0x10000
	v_add_co_u32_e64 v12, s[0:1], s0, v48
	v_mul_f32_e32 v4, v66, v39
	s_nop 0
	v_addc_co_u32_e64 v13, s[0:1], 0, v49, s[0:1]
	ds_write_b16 v237, v3
	v_mul_f32_e32 v3, v5, v39
	v_cvt_pk_bf16_f32 v3, v3, s0
	v_lshl_or_b32 v152, v3, 16, v152
	v_mul_f32_e32 v3, v5, v80
	v_cvt_pk_bf16_f32 v3, v3, s0
	v_lshl_or_b32 v154, v3, 16, v154
	v_mul_f32_e32 v3, v65, v81
	v_cvt_pk_bf16_f32 v3, v3, s0
	ds_write_b16 v236, v3 offset:128
	v_mul_f32_e32 v3, v65, v82
	v_cvt_pk_bf16_f32 v3, v3, s0
	v_cvt_pk_bf16_f32 v4, v4, s0
	ds_write_b16 v237, v3 offset:128
	v_and_b32_e32 v153, 0xffff, v4
	v_mul_f32_e32 v4, v66, v80
	v_cvt_pk_bf16_f32 v4, v4, s0
	v_and_b32_e32 v155, 0xffff, v4
	v_mul_f32_e32 v4, v8, v81
	v_cvt_pk_bf16_f32 v4, v4, s0
	ds_write_b16 v236, v4 offset:256
	v_mul_f32_e32 v4, v8, v82
	v_cvt_pk_bf16_f32 v4, v4, s0
	ds_write_b16 v237, v4 offset:256
	v_mul_f32_e32 v4, v67, v39
	v_cvt_pk_bf16_f32 v4, v4, s0
	v_lshl_or_b32 v153, v4, 16, v153
	global_store_dwordx2 v[70:71], v[152:153], off
	v_mul_f32_e32 v4, v67, v80
	v_cvt_pk_bf16_f32 v4, v4, s0
	v_lshl_or_b32 v155, v4, 16, v155
	global_store_dwordx2 v[52:53], v[154:155], off
	v_mul_f32_e32 v4, v9, v81
	v_cvt_pk_bf16_f32 v3, v8, v9
	v_cvt_pk_bf16_f32 v4, v4, s0
	v_cvt_pk_bf16_f32 v8, v60, v61
	v_lshlrev_b32_e32 v60, 1, v83
	ds_write_b16 v236, v4 offset:384
	v_mul_f32_e32 v4, v9, v82
	v_mul_f32_e32 v5, v72, v39
	v_or_b32_e32 v48, 16, v60
	v_mov_b32_e32 v49, v0
	v_cvt_pk_bf16_f32 v4, v4, s0
	v_cvt_pk_bf16_f32 v5, v5, s0
	v_lshl_add_u64 v[52:53], v[24:25], 0, v[48:49]
	ds_write_b16 v237, v4 offset:384
	v_and_b32_e32 v156, 0xffff, v5
	v_mul_f32_e32 v5, v72, v80
	v_cvt_pk_bf16_f32 v5, v5, s0
	v_lshl_add_u64 v[48:49], v[26:27], 0, v[48:49]
	v_and_b32_e32 v158, 0xffff, v5
	v_mul_f32_e32 v5, v74, v81
	v_cvt_pk_bf16_f32 v5, v5, s0
	ds_write_b16 v236, v5 offset:512
	v_mul_f32_e32 v5, v74, v82
	v_cvt_pk_bf16_f32 v5, v5, s0
	ds_write_b16 v237, v5 offset:512
	v_mul_f32_e32 v5, v73, v39
	v_or_b32_e32 v48, 18, v60
	v_mov_b32_e32 v49, v0
	v_cvt_pk_bf16_f32 v5, v5, s0
	v_lshl_add_u64 v[52:53], v[24:25], 0, v[48:49]
	v_lshl_or_b32 v156, v5, 16, v156
	v_mul_f32_e32 v5, v73, v80
	v_cvt_pk_bf16_f32 v5, v5, s0
	v_lshl_add_u64 v[48:49], v[26:27], 0, v[48:49]
	v_lshl_or_b32 v158, v5, 16, v158
	v_mul_f32_e32 v5, v75, v81
	v_cvt_pk_bf16_f32 v5, v5, s0
	v_mul_f32_e32 v48, v76, v39
	ds_write_b16 v236, v5 offset:640
	v_mul_f32_e32 v5, v75, v82
	v_cvt_pk_bf16_f32 v9, v58, v59
	v_cvt_pk_bf16_f32 v58, v48, s0
	v_or_b32_e32 v48, 20, v60
	v_mov_b32_e32 v49, v0
	v_cvt_pk_bf16_f32 v5, v5, s0
	v_lshl_add_u64 v[52:53], v[24:25], 0, v[48:49]
	ds_write_b16 v237, v5 offset:640
	v_and_b32_e32 v157, 0xffff, v58
	v_mul_f32_e32 v52, v76, v80
	v_cvt_pk_bf16_f32 v52, v52, s0
	v_lshl_add_u64 v[48:49], v[26:27], 0, v[48:49]
	v_and_b32_e32 v159, 0xffff, v52
	v_mul_f32_e32 v48, v78, v81
	v_cvt_pk_bf16_f32 v48, v48, s0
	ds_write_b16 v236, v48 offset:768
	v_mul_f32_e32 v48, v78, v82
	v_cvt_pk_bf16_f32 v48, v48, s0
	ds_write_b16 v237, v48 offset:768
	v_mul_f32_e32 v48, v77, v39
	v_cvt_pk_bf16_f32 v58, v48, s0
	v_or_b32_e32 v48, 22, v60
	v_mov_b32_e32 v49, v0
	v_lshl_add_u64 v[52:53], v[24:25], 0, v[48:49]
	v_lshl_or_b32 v157, v58, 16, v157
	global_store_dwordx2 v[52:53], v[156:157], off offset:-6
	v_mul_f32_e32 v52, v77, v80
	v_cvt_pk_bf16_f32 v52, v52, s0
	v_lshl_add_u64 v[48:49], v[26:27], 0, v[48:49]
	v_lshl_or_b32 v159, v52, 16, v159
	global_store_dwordx2 v[48:49], v[158:159], off offset:-6
	v_mul_f32_e32 v48, v79, v81
	v_cvt_pk_bf16_f32 v48, v48, s0
	v_lshlrev_b32_e32 v37, 1, v37
	ds_write_b16 v236, v48 offset:896
	v_mul_f32_e32 v48, v79, v82
	v_mul_f32_e32 v49, v50, v39
	v_or_b32_e32 v58, 32, v37
	v_mov_b32_e32 v59, v0
	v_cvt_pk_bf16_f32 v48, v48, s0
	v_cvt_pk_bf16_f32 v49, v49, s0
	v_lshl_add_u64 v[60:61], v[24:25], 0, v[58:59]
	ds_write_b16 v237, v48 offset:896
	v_and_b32_e32 v160, 0xffff, v49
	v_mul_f32_e32 v49, v50, v80
	v_cvt_pk_bf16_f32 v49, v49, s0
	v_lshl_add_u64 v[58:59], v[26:27], 0, v[58:59]
	v_cvt_pk_bf16_f32 v48, v46, v47
	v_and_b32_e32 v162, 0xffff, v49
	v_mul_f32_e32 v49, v46, v81
	v_mul_f32_e32 v46, v46, v82
	v_cvt_pk_bf16_f32 v46, v46, s0
	ds_write_b16 v237, v46 offset:1024
	v_mul_f32_e32 v46, v51, v39
	v_or_b32_e32 v58, 34, v37
	v_mov_b32_e32 v59, v0
	v_cvt_pk_bf16_f32 v49, v49, s0
	v_cvt_pk_bf16_f32 v46, v46, s0
	v_lshl_add_u64 v[60:61], v[24:25], 0, v[58:59]
	ds_write_b16 v236, v49 offset:1024
	v_lshl_or_b32 v160, v46, 16, v160
	v_mul_f32_e32 v46, v51, v80
	v_cvt_pk_bf16_f32 v52, v50, v51
	v_cvt_pk_bf16_f32 v46, v46, s0
	v_lshl_add_u64 v[50:51], v[26:27], 0, v[58:59]
	v_lshl_or_b32 v162, v46, 16, v162
	v_mul_f32_e32 v46, v47, v81
	v_cvt_pk_bf16_f32 v46, v46, s0
	ds_write_b16 v236, v46 offset:1152
	v_mul_f32_e32 v46, v47, v82
	v_cvt_pk_bf16_f32 v46, v46, s0
	ds_write_b16 v237, v46 offset:1152
	v_mul_f32_e32 v46, v44, v39
	v_cvt_pk_bf16_f32 v56, v56, v57
	v_cvt_pk_bf16_f32 v53, v44, v45
	v_cvt_pk_bf16_f32 v57, v54, v55
	v_cvt_pk_bf16_f32 v54, v46, s0
	v_or_b32_e32 v46, 36, v37
	v_mov_b32_e32 v47, v0
	v_mul_f32_e32 v44, v44, v80
	v_lshl_add_u64 v[50:51], v[24:25], 0, v[46:47]
	v_cvt_pk_bf16_f32 v44, v44, s0
	v_lshl_add_u64 v[46:47], v[26:27], 0, v[46:47]
	v_cvt_pk_bf16_f32 v49, v42, v43
	v_and_b32_e32 v161, 0xffff, v54
	v_and_b32_e32 v163, 0xffff, v44
	v_mul_f32_e32 v44, v42, v81
	v_mul_f32_e32 v42, v42, v82
	v_cvt_pk_bf16_f32 v42, v42, s0
	v_cvt_pk_bf16_f32 v44, v44, s0
	ds_write_b16 v237, v42 offset:1280
	v_mul_f32_e32 v42, v45, v39
	v_or_b32_e32 v46, 38, v37
	v_mov_b32_e32 v47, v0
	v_mul_f32_e32 v37, v45, v80
	ds_write_b16 v236, v44 offset:1280
	v_cvt_pk_bf16_f32 v42, v42, s0
	v_lshl_add_u64 v[50:51], v[24:25], 0, v[46:47]
	v_cvt_pk_bf16_f32 v37, v37, s0
	v_lshl_add_u64 v[44:45], v[26:27], 0, v[46:47]
	v_lshl_or_b32 v161, v42, 16, v161
	global_store_dwordx2 v[50:51], v[160:161], off offset:-6
	v_lshl_or_b32 v163, v37, 16, v163
	global_store_dwordx2 v[44:45], v[162:163], off offset:-6
	v_mul_f32_e32 v37, v43, v81
	v_cvt_pk_bf16_f32 v37, v37, s0
	v_mul_u32_u24_e32 v2, 20, v69
	ds_write_b16 v236, v37 offset:1408
	v_mul_f32_e32 v37, v43, v82
	v_lshlrev_b32_e32 v84, 1, v2
	v_cvt_pk_bf16_f32 v37, v37, s0
	v_cvt_pk_bf16_f32 v58, v22, v23
	v_mul_f32_e32 v22, v30, v39
	ds_write_b16 v237, v37 offset:1408
	v_cvt_pk_bf16_f32 v54, v30, v31
	v_cvt_pk_bf16_f32 v37, v22, s0
	v_or_b32_e32 v22, 48, v84
	v_mov_b32_e32 v23, v0
	v_mul_f32_e32 v30, v30, v80
	v_lshl_add_u64 v[42:43], v[24:25], 0, v[22:23]
	v_cvt_pk_bf16_f32 v30, v30, s0
	v_lshl_add_u64 v[22:23], v[26:27], 0, v[22:23]
	v_and_b32_e32 v164, 0xffff, v37
	v_and_b32_e32 v166, 0xffff, v30
	v_mul_f32_e32 v22, v28, v81
	v_cvt_pk_bf16_f32 v22, v22, s0
	ds_write_b16 v236, v22 offset:1536
	v_mul_f32_e32 v22, v28, v82
	v_cvt_pk_bf16_f32 v22, v22, s0
	ds_write_b16 v237, v22 offset:1536
	v_mul_f32_e32 v22, v31, v39
	v_cvt_pk_bf16_f32 v50, v28, v29
	v_cvt_pk_bf16_f32 v28, v22, s0
	v_or_b32_e32 v22, 50, v84
	v_mov_b32_e32 v23, v0
	v_lshl_add_u64 v[42:43], v[24:25], 0, v[22:23]
	v_lshl_or_b32 v164, v28, 16, v164
	v_mul_f32_e32 v28, v31, v80
	v_cvt_pk_bf16_f32 v28, v28, s0
	v_lshl_add_u64 v[22:23], v[26:27], 0, v[22:23]
	v_lshl_or_b32 v166, v28, 16, v166
	v_mul_f32_e32 v22, v29, v81
	v_cvt_pk_bf16_f32 v22, v22, s0
	ds_write_b16 v236, v22 offset:1664
	v_mul_f32_e32 v22, v29, v82
	v_cvt_pk_bf16_f32 v59, v18, v19
	v_mul_f32_e32 v18, v20, v39
	v_cvt_pk_bf16_f32 v22, v22, s0
	v_cvt_pk_bf16_f32 v55, v20, v21
	v_cvt_pk_bf16_f32 v28, v18, s0
	v_or_b32_e32 v18, 52, v84
	v_mov_b32_e32 v19, v0
	v_mul_f32_e32 v20, v20, v80
	ds_write_b16 v237, v22 offset:1664
	v_lshl_add_u64 v[22:23], v[24:25], 0, v[18:19]
	v_cvt_pk_bf16_f32 v20, v20, s0
	v_lshl_add_u64 v[18:19], v[26:27], 0, v[18:19]
	v_cvt_pk_bf16_f32 v51, v16, v17
	v_and_b32_e32 v165, 0xffff, v28
	v_and_b32_e32 v167, 0xffff, v20
	v_mul_f32_e32 v18, v16, v81
	v_mul_f32_e32 v16, v16, v82
	v_cvt_pk_bf16_f32 v18, v18, s0
	v_cvt_pk_bf16_f32 v16, v16, s0
	ds_write_b16 v236, v18 offset:1792
	ds_write_b16 v237, v16 offset:1792
	v_mul_f32_e32 v16, v21, v39
	v_or_b32_e32 v18, 54, v84
	v_mov_b32_e32 v19, v0
	v_cvt_pk_bf16_f32 v16, v16, s0
	v_lshl_add_u64 v[22:23], v[24:25], 0, v[18:19]
	v_lshl_or_b32 v165, v16, 16, v165
	global_store_dwordx2 v[22:23], v[164:165], off offset:-6
	v_mul_f32_e32 v16, v21, v80
	v_cvt_pk_bf16_f32 v16, v16, s0
	v_lshl_add_u64 v[18:19], v[26:27], 0, v[18:19]
	v_lshl_or_b32 v167, v16, 16, v167
	global_store_dwordx2 v[18:19], v[166:167], off offset:-6
	v_mul_f32_e32 v16, v17, v81
	v_cvt_pk_bf16_f32 v16, v16, s0
	ds_write_b16 v236, v16 offset:1920
	v_mul_f32_e32 v16, v17, v82
	v_cvt_pk_bf16_f32 v16, v16, s0
	ds_write_b16 v237, v16 offset:1920
	v_mul_lo_u32 v16, v35, s39
	v_lshlrev_b32_e32 v17, 5, v69
	s_mov_b32 s98, 0x800000
	v_cvt_pk_bf16_f32 v2, v64, v65
	v_cvt_pk_bf16_f32 v4, v74, v75
	v_cvt_pk_bf16_f32 v5, v78, v79
	v_add3_u32 v16, 0, v16, v17
	v_cmp_eq_u32_e64 s[0:1], 0, v1
	v_cvt_pk_bf16_f32 v11, v66, v67
	v_cvt_pk_bf16_f32 v7, v62, v63
	v_cvt_pk_bf16_f32 v12, v72, v73
	v_cvt_pk_bf16_f32 v13, v76, v77
	ds_write_b128 v16, v[2:5] offset:33280
	ds_write_b128 v16, v[10:13] offset:42496
	ds_write_b128 v16, v[6:9] offset:51712
	ds_write_b128 v16, v[2:5] offset:60928
	ds_write_b128 v16, v[48:51] offset:33296
	ds_write_b128 v16, v[52:55] offset:42512
	ds_write_b128 v16, v[56:59] offset:51728
	ds_write_b128 v16, v[48:51] offset:60944
	s_and_saveexec_b64 s[12:13], s[0:1]
	s_cbranch_execz .LBB0_243
	s_lshl_b32 s0, s10, 1
	s_ashr_i32 s1, s0, 31
	s_lshl_b64 s[0:1], s[0:1], 2
	v_readlane_b32 s40, v248, 21
	v_readlane_b32 s41, v248, 22
	s_add_u32 s0, s40, s0
	s_addc_u32 s1, s41, s1
	global_store_dwordx2 v0, v[14:15], s[0:1]
.LBB0_243:
	s_or_b64 exec, exec, s[12:13]
	v_and_b32_e32 v37, 15, v1
	v_lshlrev_b32_e32 v43, 4, v68
	v_and_b32_e32 v3, 48, v34
	v_or_b32_e32 v2, v43, v37
	v_add_u32_e32 v42, 0, v3
	s_waitcnt lgkmcnt(0)
	s_barrier
	v_and_b32_e32 v244, 0x7f, v1
	v_lshrrev_b32_e32 v238, 7, v1
	v_mul_u32_u24_e32 v238, 0x840, v238
	v_lshl_add_u32 v244, v244, 4, v238
	ds_read_b128 v[152:155], v244
	ds_read_b128 v[156:159], v244 offset:4224
	ds_read_b128 v[160:163], v244 offset:8448
	ds_read_b128 v[164:167], v244 offset:12672
	v_mad_u64_u32 v[40:41], s[0:1], v2, s39, v[42:43]
	ds_read_b128 v[2:5], v40 offset:33280
	v_mul_u32_u24_e32 v6, 0x48, v37
	v_lshl_add_u32 v35, v6, 1, v42
	ds_read_b128 v[6:9], v35 offset:42496
	ds_read_b128 v[10:13], v35 offset:33280
	ds_read_b128 v[14:17], v35 offset:44800
	ds_read_b128 v[18:21], v35 offset:35584
	ds_read_b128 v[22:25], v35 offset:47104
	ds_read_b128 v[26:29], v35 offset:37888
	s_waitcnt lgkmcnt(1)
	v_mfma_f32_16x16x32_bf16 v[46:49], v[2:5], v[22:25], 0
	global_store_dwordx4 v242, v[152:155], s[24:25] offset:-2048
	global_store_dwordx4 v242, v[156:159], s[24:25] offset:2048
	global_store_dwordx4 v243, v[160:163], s[24:25] offset:-2048
	global_store_dwordx4 v243, v[164:167], s[24:25] offset:2048
	s_add_i32 s2, 0, 0x11200
	v_lshlrev_b32_e32 v41, 2, v37
	s_add_i32 s11, 0, 0x11400
	s_waitcnt lgkmcnt(0)
	v_mfma_f32_16x16x32_bf16 v[50:53], v[2:5], v[26:29], 0
	ds_read_b128 v[22:25], v35 offset:49408
	ds_read_b128 v[26:29], v35 offset:40192
	v_lshrrev_b32_e32 v45, 4, v34
	v_lshl_or_b32 v44, v45, 2, v43
	v_mfma_f32_16x16x32_bf16 v[6:9], v[2:5], v[6:9], 0
	v_cmp_lt_i32_e64 s[40:41], v37, v44
	v_cmp_ge_i32_e64 s[0:1], v37, v44
	v_mfma_f32_16x16x32_bf16 v[10:13], v[2:5], v[10:13], 0
	v_mfma_f32_16x16x32_bf16 v[14:17], v[2:5], v[14:17], 0
	v_mfma_f32_16x16x32_bf16 v[18:21], v[2:5], v[18:21], 0
	s_waitcnt lgkmcnt(1)
	v_mfma_f32_16x16x32_bf16 v[54:57], v[2:5], v[22:25], 0
	s_waitcnt lgkmcnt(0)
	v_mfma_f32_16x16x32_bf16 v[2:5], v[2:5], v[26:29], 0
	ds_read_b128 v[58:61], v40 offset:33344
	ds_read_b128 v[22:25], v35 offset:42560
	ds_read_b128 v[26:29], v35 offset:33344
	s_waitcnt lgkmcnt(1)
	v_mfma_f32_16x16x32_bf16 v[30:33], v[58:61], v[22:25], v[6:9]
	s_waitcnt lgkmcnt(0)
	v_mfma_f32_16x16x32_bf16 v[26:29], v[58:61], v[26:29], v[10:13]
	s_nop 0
	ds_read_b128 v[6:9], v35 offset:44864
	s_nop 0
	ds_read_b128 v[10:13], v35 offset:35648
	s_waitcnt lgkmcnt(1)
	v_mfma_f32_16x16x32_bf16 v[22:25], v[58:61], v[6:9], v[14:17]
	s_waitcnt lgkmcnt(0)
	v_mfma_f32_16x16x32_bf16 v[18:21], v[58:61], v[10:13], v[18:21]
	ds_read_b128 v[6:9], v35 offset:47168
	ds_read_b128 v[10:13], v35 offset:37952
	s_waitcnt lgkmcnt(1)
	v_mfma_f32_16x16x32_bf16 v[14:17], v[58:61], v[6:9], v[46:49]
	ds_read_b128 v[6:9], v35 offset:49472
	s_nop 1
	ds_read_b128 v[46:49], v35 offset:40256
	v_add_u32_e32 v35, s2, v41
	s_waitcnt lgkmcnt(0)
	s_barrier
	s_waitcnt lgkmcnt(0)
	v_mfma_f32_16x16x32_bf16 v[2:5], v[58:61], v[46:49], v[2:5]
	v_add_u32_e32 v47, s11, v41
	ds_read_b32 v39, v35
	v_mfma_f32_16x16x32_bf16 v[6:9], v[58:61], v[6:9], v[54:57]
	s_nop 2
	ds_read_b32 v57, v47
	v_or_b32_e32 v35, 0x100, v41
	v_mfma_f32_16x16x32_bf16 v[10:13], v[58:61], v[10:13], v[50:53]
	v_add_u32_e32 v46, s2, v35
	v_add_u32_e32 v35, s11, v35
	ds_read_b32 v46, v46
	ds_read_b32 v58, v35
	v_lshl_add_u32 v51, v44, 2, s2
	ds_read_b32 v35, v51 offset:256
	v_mov_b32_e32 v47, 0
	v_mov_b32_e32 v61, 0
	s_and_saveexec_b64 s[12:13], s[0:1]
	s_cbranch_execz .LBB0_245
	ds_read_b32 v48, v51
	s_waitcnt lgkmcnt(0)
	v_sub_f32_e32 v48, v39, v48
	v_mul_f32_e32 v48, 0x3fb8aa3b, v48
	v_exp_f32_e32 v61, v48
